# P9 row pass walks each wave's rows from last to first (rows written last by the up GEMM are read first: Infinity Cache hits)
# baseline (speedup 1.0000x reference)
; #define SEAM(k) do { if (IN(k) && IN((k) + 1)) xcd_barrier(bar); } while (0)
;     constexpr int RL = 2048 * NC;
;     for (int r = gw; r < R; r += NGW) { const bf16_t* sr = src + (size_t)r * RL; u32x4 pk[NC][4]; float mx = 0.f;
; __global__ void __launch_bounds__(512, 2) mk_fwd(Args args) {
;     ...
;     if (IN(9)) { rotq_rows_i8(WSP(bf16_t, WS_ACT), WSP(unsigned char, WS_ACTQ), WSP(float, WS_SA4), M, F.wave * F.G + (int)blockIdx.x, F.G * 8, F.lane); } SEAM(9);
.LBB0_2798:
	s_cmp_lt_i32 s90, 10
	s_cselect_b64 s[0:1], -1, 0
	s_and_b64 s[0:1], s[0:1], s[2:3]
	s_andn2_b64 vcc, exec, s[0:1]
	s_cbranch_vccnz .LBB0_2804
	s_add_i32 s13, s66, s92
	s_cmpk_gt_i32 s13, 0x21ff
	s_cbranch_scc1 .LBB0_2804
	s_lshl_b32 s2, s96, 3
	s_ashr_i32 s3, s92, 31
	s_ashr_i32 s6, s66, 31
	s_add_u32 s10, s92, s66
	s_addc_u32 s11, s3, s6
	s_lshl_b64 s[6:7], s[10:11], 2
	s_add_u32 s16, s6, 0x19153000
	s_addc_u32 s17, s7, 0
	s_ashr_i32 s3, s2, 31
	s_lshl_b64 s[6:7], s[2:3], 2
	s_mul_i32 s3, s11, 0x6000
	s_mul_hi_u32 s8, s10, 0x6000
	s_add_i32 s8, s8, s3
	s_mul_i32 s3, s10, 0x6000
	v_mbcnt_lo_u32_b32 v1, -1, 0
	v_lshl_or_b32 v82, v238, 4, s3
	s_mul_i32 s3, s11, 0x3000
	s_mul_hi_u32 s11, s10, 0x3000
	v_mbcnt_hi_u32_b32 v1, -1, v1
	s_add_i32 s11, s11, s3
	s_mul_i32 s3, s10, 0x3000
	s_waitcnt vmcnt(0)
	v_and_b32_e32 v2, 64, v1
	v_cmp_eq_u32_e64 s[4:5], 0, v238
	v_mov_b32_e32 v83, s8
	s_mul_i32 s8, s96, 0x30000
	s_mul_hi_i32 s9, s2, 0x6000
	v_lshl_or_b32 v84, v238, 3, s3
	v_mov_b32_e32 v85, s11
	s_mul_i32 s10, s96, 0x18000
	s_mul_hi_i32 s11, s2, 0x3000
	v_add_u32_e32 v86, 64, v2
	v_xor_b32_e32 v87, 1, v1
	v_xor_b32_e32 v88, 2, v1
	v_xor_b32_e32 v89, 4, v1
	v_xor_b32_e32 v90, 8, v1
	v_xor_b32_e32 v91, 16, v1
	v_xor_b32_e32 v92, 32, v1
	v_mov_b32_e32 v93, 0
	s_mov_b32 s3, 0x42fe0000
	s_mov_b32 s12, 0x4b400000
	s_mov_b32 s18, 0x5090f000
	s_mov_b32 s19, 0x50910000
	s_mov_b32 s20, 0x50911000
	s_cmpk_lg_i32 s96, 0x100
	s_cbranch_scc1 .Lp9_fwd
	s_cmp_lt_i32 s13, 0x200
	s_cselect_b32 s98, 4, 3
	s_lshl_b32 s99, s98, 11
	s_add_i32 s13, s13, s99
	s_lshl_b32 s99, s98, 13
	s_add_u32 s16, s16, s99
	s_addc_u32 s17, s17, 0
	s_mul_i32 s100, s98, 0x3000000
	s_mov_b32 s101, 0
	v_lshl_add_u64 v[82:83], v[82:83], 0, s[100:101]
	s_mul_i32 s100, s98, 0x1800000
	v_lshl_add_u64 v[84:85], v[84:85], 0, s[100:101]
	s_mov_b32 s2, 0xfffff800
	s_mov_b32 s6, 0xffffe000
	s_mov_b32 s7, -1
	s_mov_b32 s8, 0xfd000000
	s_mov_b32 s9, -1
	s_mov_b32 s10, 0xfe800000
	s_mov_b32 s11, -1

; __device__ __forceinline__ float bf_lo(unsigned w) { return __uint_as_float(w << 16); }
; __device__ __forceinline__ float bf_hi(unsigned w) { return __uint_as_float(w & 0xffff0000u); }
; __device__ __forceinline__ unsigned q8_pack4(float a, float b, float c, float d, float inv) {
;     const unsigned ua = __float_as_uint(fmaf(a, inv, 12582912.0f)), ub = __float_as_uint(fmaf(b, inv, 12582912.0f)), uc = __float_as_uint(fmaf(c, inv, 12582912.0f)), ud = __float_as_uint(fmaf(d, inv, 12582912.0f));
;     return (ua & 255u) | ((ub & 255u) << 8) | ((uc & 255u) << 16) | (ud << 24);
;     ...
;         const float inv = 127.0f / mx;
; #pragma unroll
;         for (int i = 0; i < NC; ++i) { unsigned char* d = dst + (size_t)r * RL + 2048 * i + 8 * lane;
; #pragma unroll
;             for (int q = 0; q < 4; ++q) { const u32x4 w = pk[i][q]; u32x2 o; o.x = q8_pack4(bf_lo(w.x), bf_hi(w.x), bf_lo(w.y), bf_hi(w.y), inv); o.y = q8_pack4(bf_lo(w.z), bf_hi(w.z), bf_lo(w.w), bf_hi(w.w), inv);
;                 *(u32x2*)(d + 512 * q) = o; } } }
.LBB0_2801:
	s_or_b64 exec, exec, s[14:15]
	v_div_scale_f32 v4, s[14:15], v2, v2, s3
	v_rcp_f32_e32 v5, v4
	v_div_scale_f32 v6, vcc, s3, v2, s3
	v_and_b32_e32 v9, 0xffff0000, v109
	v_fma_f32 v7, -v4, v5, 1.0
	v_fmac_f32_e32 v5, v7, v5
	v_mul_f32_e32 v7, v6, v5
	v_fma_f32 v8, -v4, v7, v6
	v_fmac_f32_e32 v7, v8, v5
	v_fma_f32 v4, -v4, v7, v6
	v_div_fmas_f32 v4, v4, v5, v7
	v_div_fixup_f32 v2, v4, v2, s3
	v_and_b32_e32 v8, 0xffff0000, v107
	v_and_b32_e32 v33, 0xffff0000, v108
	v_and_b32_e32 v32, 0xffff0000, v106
	v_lshlrev_b32_e32 v7, 16, v109
	v_lshlrev_b32_e32 v6, 16, v107
	v_lshlrev_b32_e32 v31, 16, v108
	v_lshlrev_b32_e32 v30, 16, v106
	v_pk_fma_f32 v[8:9], v[8:9], v[2:3], s[12:13] op_sel_hi:[1,0,0]
	v_pk_fma_f32 v[32:33], v[32:33], v[2:3], s[12:13] op_sel_hi:[1,0,0]
	v_pk_fma_f32 v[6:7], v[6:7], v[2:3], s[12:13] op_sel_hi:[1,0,0]
	v_pk_fma_f32 v[30:31], v[30:31], v[2:3], s[12:13] op_sel_hi:[1,0,0]
	v_lshlrev_b32_e32 v8, 8, v8
	v_lshlrev_b32_e32 v32, 24, v32
	v_lshl_add_u64 v[4:5], s[86:87], 0, v[84:85]
	v_lshlrev_b32_e32 v9, 8, v9
	v_and_b32_e32 v8, 0xff00, v8
	v_lshlrev_b32_e32 v29, 16, v31
	v_lshlrev_b32_e32 v31, 24, v33
	v_or_b32_sdwa v6, v32, v6 dst_sel:DWORD dst_unused:UNUSED_PAD src0_sel:DWORD src1_sel:BYTE_0
	v_and_b32_e32 v9, 0xff00, v9
	v_lshlrev_b32_e32 v30, 16, v30
	v_or_b32_sdwa v7, v31, v7 dst_sel:DWORD dst_unused:UNUSED_PAD src0_sel:DWORD src1_sel:BYTE_0
	v_or_b32_e32 v6, v6, v8
	v_add_co_u32_e32 v8, vcc, s18, v4
	v_and_b32_e32 v30, 0xff0000, v30
	v_or_b32_e32 v7, v7, v9
	v_addc_co_u32_e32 v9, vcc, 0, v5, vcc
	v_and_b32_e32 v29, 0xff0000, v29
	v_or_b32_e32 v30, v6, v30
	v_add_co_u32_e32 v6, vcc, s19, v4
	v_or_b32_e32 v31, v7, v29
	s_nop 0
	v_addc_co_u32_e32 v7, vcc, 0, v5, vcc
	global_store_dwordx2 v[6:7], v[30:31], off offset:-4096
	v_lshlrev_b32_e32 v30, 16, v103
	v_and_b32_e32 v33, 0xffff0000, v105
	v_and_b32_e32 v32, 0xffff0000, v103
	v_lshlrev_b32_e32 v106, 16, v102
	v_and_b32_e32 v103, 0xffff0000, v104
	v_and_b32_e32 v102, 0xffff0000, v102
	v_lshlrev_b32_e32 v31, 16, v105
	v_lshlrev_b32_e32 v107, 16, v104
	v_pk_fma_f32 v[32:33], v[32:33], v[2:3], s[12:13] op_sel_hi:[1,0,0]
	v_pk_fma_f32 v[102:103], v[102:103], v[2:3], s[12:13] op_sel_hi:[1,0,0]
	v_pk_fma_f32 v[30:31], v[30:31], v[2:3], s[12:13] op_sel_hi:[1,0,0]
	v_pk_fma_f32 v[104:105], v[106:107], v[2:3], s[12:13] op_sel_hi:[1,0,0]
	v_lshlrev_b32_e32 v29, 8, v33
	v_lshlrev_b32_e32 v32, 8, v32
	v_lshlrev_b32_e32 v103, 24, v103
	v_lshlrev_b32_e32 v102, 24, v102
	v_and_b32_e32 v29, 0xff00, v29
	v_and_b32_e32 v32, 0xff00, v32
	v_lshlrev_b32_e32 v33, 16, v105
	v_lshlrev_b32_e32 v104, 16, v104
	v_or_b32_sdwa v31, v103, v31 dst_sel:DWORD dst_unused:UNUSED_PAD src0_sel:DWORD src1_sel:BYTE_0
	v_or_b32_sdwa v30, v102, v30 dst_sel:DWORD dst_unused:UNUSED_PAD src0_sel:DWORD src1_sel:BYTE_0
	v_and_b32_e32 v33, 0xff0000, v33
	v_and_b32_e32 v104, 0xff0000, v104
	v_or_b32_e32 v29, v31, v29
	v_or_b32_e32 v30, v30, v32
	v_or_b32_e32 v31, v29, v33
	v_or_b32_e32 v30, v30, v104
	global_store_dwordx2 v[8:9], v[30:31], off offset:512
	v_lshlrev_b32_e32 v30, 16, v99
	v_and_b32_e32 v33, 0xffff0000, v101
	v_and_b32_e32 v32, 0xffff0000, v99
	v_lshlrev_b32_e32 v102, 16, v98
	v_and_b32_e32 v99, 0xffff0000, v100
	v_and_b32_e32 v98, 0xffff0000, v98
	v_lshlrev_b32_e32 v31, 16, v101
	v_lshlrev_b32_e32 v103, 16, v100
	v_pk_fma_f32 v[32:33], v[32:33], v[2:3], s[12:13] op_sel_hi:[1,0,0]
	v_pk_fma_f32 v[98:99], v[98:99], v[2:3], s[12:13] op_sel_hi:[1,0,0]
	v_pk_fma_f32 v[30:31], v[30:31], v[2:3], s[12:13] op_sel_hi:[1,0,0]
	v_pk_fma_f32 v[100:101], v[102:103], v[2:3], s[12:13] op_sel_hi:[1,0,0]
	v_lshlrev_b32_e32 v29, 8, v33
	v_lshlrev_b32_e32 v32, 8, v32
	v_lshlrev_b32_e32 v99, 24, v99
	v_lshlrev_b32_e32 v98, 24, v98
	v_and_b32_e32 v29, 0xff00, v29
	v_and_b32_e32 v32, 0xff00, v32
	v_lshlrev_b32_e32 v33, 16, v101
	v_lshlrev_b32_e32 v100, 16, v100
	v_or_b32_sdwa v31, v99, v31 dst_sel:DWORD dst_unused:UNUSED_PAD src0_sel:DWORD src1_sel:BYTE_0
	v_or_b32_sdwa v30, v98, v30 dst_sel:DWORD dst_unused:UNUSED_PAD src0_sel:DWORD src1_sel:BYTE_0
	v_and_b32_e32 v33, 0xff0000, v33
	v_and_b32_e32 v100, 0xff0000, v100
	v_or_b32_e32 v29, v31, v29
	v_or_b32_e32 v30, v30, v32
	v_or_b32_e32 v31, v29, v33
	v_or_b32_e32 v30, v30, v100
	global_store_dwordx2 v[8:9], v[30:31], off offset:1024
	v_lshlrev_b32_e32 v30, 16, v95
	v_and_b32_e32 v33, 0xffff0000, v97
	v_and_b32_e32 v32, 0xffff0000, v95
	v_lshlrev_b32_e32 v98, 16, v94
	v_and_b32_e32 v95, 0xffff0000, v96
	v_and_b32_e32 v94, 0xffff0000, v94
	v_lshlrev_b32_e32 v31, 16, v97
	v_lshlrev_b32_e32 v99, 16, v96
	v_pk_fma_f32 v[32:33], v[32:33], v[2:3], s[12:13] op_sel_hi:[1,0,0]
	v_pk_fma_f32 v[94:95], v[94:95], v[2:3], s[12:13] op_sel_hi:[1,0,0]
	v_pk_fma_f32 v[30:31], v[30:31], v[2:3], s[12:13] op_sel_hi:[1,0,0]
	v_pk_fma_f32 v[96:97], v[98:99], v[2:3], s[12:13] op_sel_hi:[1,0,0]
	v_lshlrev_b32_e32 v29, 8, v33
	v_lshlrev_b32_e32 v32, 8, v32
	v_lshlrev_b32_e32 v95, 24, v95
	v_lshlrev_b32_e32 v94, 24, v94
	v_and_b32_e32 v29, 0xff00, v29
	v_and_b32_e32 v32, 0xff00, v32
	v_lshlrev_b32_e32 v33, 16, v97
	v_lshlrev_b32_e32 v96, 16, v96
	v_or_b32_sdwa v31, v95, v31 dst_sel:DWORD dst_unused:UNUSED_PAD src0_sel:DWORD src1_sel:BYTE_0
	v_or_b32_sdwa v30, v94, v30 dst_sel:DWORD dst_unused:UNUSED_PAD src0_sel:DWORD src1_sel:BYTE_0
	v_and_b32_e32 v33, 0xff0000, v33
	v_and_b32_e32 v96, 0xff0000, v96
	v_or_b32_e32 v29, v31, v29
	v_or_b32_e32 v30, v30, v32
	v_or_b32_e32 v31, v29, v33
	v_or_b32_e32 v30, v30, v96
	global_store_dwordx2 v[8:9], v[30:31], off offset:1536
	v_lshlrev_b32_e32 v30, 16, v79
	v_and_b32_e32 v33, 0xffff0000, v81
	v_and_b32_e32 v32, 0xffff0000, v79
	v_lshlrev_b32_e32 v94, 16, v78
; __device__ __forceinline__ float bf_lo(unsigned w) { return __uint_as_float(w << 16); }
; __device__ __forceinline__ float bf_hi(unsigned w) { return __uint_as_float(w & 0xffff0000u); }
; __device__ __forceinline__ unsigned q8_pack4(float a, float b, float c, float d, float inv) {
;     const unsigned ua = __float_as_uint(fmaf(a, inv, 12582912.0f)), ub = __float_as_uint(fmaf(b, inv, 12582912.0f)), uc = __float_as_uint(fmaf(c, inv, 12582912.0f)), ud = __float_as_uint(fmaf(d, inv, 12582912.0f));
;     return (ua & 255u) | ((ub & 255u) << 8) | ((uc & 255u) << 16) | (ud << 24);
;     ...
;         for (int i = 0; i < NC; ++i) { unsigned char* d = dst + (size_t)r * RL + 2048 * i + 8 * lane;
; #pragma unroll
;             for (int q = 0; q < 4; ++q) { const u32x4 w = pk[i][q]; u32x2 o; o.x = q8_pack4(bf_lo(w.x), bf_hi(w.x), bf_lo(w.y), bf_hi(w.y), inv); o.y = q8_pack4(bf_lo(w.z), bf_hi(w.z), bf_lo(w.w), bf_hi(w.w), inv);
;                 *(u32x2*)(d + 512 * q) = o; } } }
	v_and_b32_e32 v79, 0xffff0000, v80
	v_and_b32_e32 v78, 0xffff0000, v78
	v_lshlrev_b32_e32 v31, 16, v81
	v_lshlrev_b32_e32 v95, 16, v80
	v_pk_fma_f32 v[32:33], v[32:33], v[2:3], s[12:13] op_sel_hi:[1,0,0]
	v_pk_fma_f32 v[78:79], v[78:79], v[2:3], s[12:13] op_sel_hi:[1,0,0]
	v_pk_fma_f32 v[30:31], v[30:31], v[2:3], s[12:13] op_sel_hi:[1,0,0]
	v_pk_fma_f32 v[80:81], v[94:95], v[2:3], s[12:13] op_sel_hi:[1,0,0]
	v_lshlrev_b32_e32 v29, 8, v33
	v_lshlrev_b32_e32 v32, 8, v32
	v_lshlrev_b32_e32 v79, 24, v79
	v_lshlrev_b32_e32 v78, 24, v78
	v_and_b32_e32 v29, 0xff00, v29
	v_and_b32_e32 v32, 0xff00, v32
	v_lshlrev_b32_e32 v33, 16, v81
	v_lshlrev_b32_e32 v80, 16, v80
	v_or_b32_sdwa v31, v79, v31 dst_sel:DWORD dst_unused:UNUSED_PAD src0_sel:DWORD src1_sel:BYTE_0
	v_or_b32_sdwa v30, v78, v30 dst_sel:DWORD dst_unused:UNUSED_PAD src0_sel:DWORD src1_sel:BYTE_0
	v_and_b32_e32 v33, 0xff0000, v33
	v_and_b32_e32 v80, 0xff0000, v80
	v_or_b32_e32 v29, v31, v29
	v_or_b32_e32 v30, v30, v32
	v_or_b32_e32 v31, v29, v33
	v_or_b32_e32 v30, v30, v80
	global_store_dwordx2 v[8:9], v[30:31], off offset:2048
	v_lshlrev_b32_e32 v30, 16, v75
	v_and_b32_e32 v33, 0xffff0000, v77
	v_and_b32_e32 v32, 0xffff0000, v75
	v_lshlrev_b32_e32 v78, 16, v74
	v_and_b32_e32 v75, 0xffff0000, v76
	v_and_b32_e32 v74, 0xffff0000, v74
	v_lshlrev_b32_e32 v31, 16, v77
	v_lshlrev_b32_e32 v79, 16, v76
	v_pk_fma_f32 v[32:33], v[32:33], v[2:3], s[12:13] op_sel_hi:[1,0,0]
	v_pk_fma_f32 v[74:75], v[74:75], v[2:3], s[12:13] op_sel_hi:[1,0,0]
	v_pk_fma_f32 v[30:31], v[30:31], v[2:3], s[12:13] op_sel_hi:[1,0,0]
	v_pk_fma_f32 v[76:77], v[78:79], v[2:3], s[12:13] op_sel_hi:[1,0,0]
	v_lshlrev_b32_e32 v29, 8, v33
	v_lshlrev_b32_e32 v32, 8, v32
	v_lshlrev_b32_e32 v75, 24, v75
	v_lshlrev_b32_e32 v74, 24, v74
	v_and_b32_e32 v29, 0xff00, v29
	v_and_b32_e32 v32, 0xff00, v32
	v_lshlrev_b32_e32 v33, 16, v77
	v_lshlrev_b32_e32 v76, 16, v76
	v_or_b32_sdwa v31, v75, v31 dst_sel:DWORD dst_unused:UNUSED_PAD src0_sel:DWORD src1_sel:BYTE_0
	v_or_b32_sdwa v30, v74, v30 dst_sel:DWORD dst_unused:UNUSED_PAD src0_sel:DWORD src1_sel:BYTE_0
	v_and_b32_e32 v33, 0xff0000, v33
	v_and_b32_e32 v76, 0xff0000, v76
	v_or_b32_e32 v29, v31, v29
	v_or_b32_e32 v30, v30, v32
	v_or_b32_e32 v31, v29, v33
	v_or_b32_e32 v30, v30, v76
	global_store_dwordx2 v[8:9], v[30:31], off offset:2560
	v_lshlrev_b32_e32 v30, 16, v71
	v_and_b32_e32 v33, 0xffff0000, v73
	v_and_b32_e32 v32, 0xffff0000, v71
	v_lshlrev_b32_e32 v74, 16, v70
	v_and_b32_e32 v71, 0xffff0000, v72
	v_and_b32_e32 v70, 0xffff0000, v70
	v_lshlrev_b32_e32 v31, 16, v73
	v_lshlrev_b32_e32 v75, 16, v72
	v_pk_fma_f32 v[32:33], v[32:33], v[2:3], s[12:13] op_sel_hi:[1,0,0]
	v_pk_fma_f32 v[70:71], v[70:71], v[2:3], s[12:13] op_sel_hi:[1,0,0]
	v_pk_fma_f32 v[30:31], v[30:31], v[2:3], s[12:13] op_sel_hi:[1,0,0]
	v_pk_fma_f32 v[72:73], v[74:75], v[2:3], s[12:13] op_sel_hi:[1,0,0]
	v_lshlrev_b32_e32 v29, 8, v33
	v_lshlrev_b32_e32 v32, 8, v32
	v_lshlrev_b32_e32 v71, 24, v71
	v_lshlrev_b32_e32 v70, 24, v70
	v_and_b32_e32 v29, 0xff00, v29
	v_and_b32_e32 v32, 0xff00, v32
	v_lshlrev_b32_e32 v33, 16, v73
	v_lshlrev_b32_e32 v72, 16, v72
	v_or_b32_sdwa v31, v71, v31 dst_sel:DWORD dst_unused:UNUSED_PAD src0_sel:DWORD src1_sel:BYTE_0
	v_or_b32_sdwa v30, v70, v30 dst_sel:DWORD dst_unused:UNUSED_PAD src0_sel:DWORD src1_sel:BYTE_0
	v_and_b32_e32 v33, 0xff0000, v33
	v_and_b32_e32 v72, 0xff0000, v72
	v_or_b32_e32 v29, v31, v29
	v_or_b32_e32 v30, v30, v32
	v_or_b32_e32 v31, v29, v33
	v_or_b32_e32 v30, v30, v72
	global_store_dwordx2 v[8:9], v[30:31], off offset:3072
	v_lshlrev_b32_e32 v30, 16, v67
	v_and_b32_e32 v33, 0xffff0000, v69
	v_and_b32_e32 v32, 0xffff0000, v67
	v_lshlrev_b32_e32 v70, 16, v66
	v_and_b32_e32 v67, 0xffff0000, v68
	v_and_b32_e32 v66, 0xffff0000, v66
	v_lshlrev_b32_e32 v31, 16, v69
	v_lshlrev_b32_e32 v71, 16, v68
	v_pk_fma_f32 v[32:33], v[32:33], v[2:3], s[12:13] op_sel_hi:[1,0,0]
	v_pk_fma_f32 v[66:67], v[66:67], v[2:3], s[12:13] op_sel_hi:[1,0,0]
	v_pk_fma_f32 v[30:31], v[30:31], v[2:3], s[12:13] op_sel_hi:[1,0,0]
	v_pk_fma_f32 v[68:69], v[70:71], v[2:3], s[12:13] op_sel_hi:[1,0,0]
	v_lshlrev_b32_e32 v29, 8, v33
	v_lshlrev_b32_e32 v32, 8, v32
	v_lshlrev_b32_e32 v67, 24, v67
	v_lshlrev_b32_e32 v66, 24, v66
	v_and_b32_e32 v29, 0xff00, v29
	v_and_b32_e32 v32, 0xff00, v32
	v_lshlrev_b32_e32 v33, 16, v69
	v_lshlrev_b32_e32 v68, 16, v68
	v_or_b32_sdwa v31, v67, v31 dst_sel:DWORD dst_unused:UNUSED_PAD src0_sel:DWORD src1_sel:BYTE_0
	v_or_b32_sdwa v30, v66, v30 dst_sel:DWORD dst_unused:UNUSED_PAD src0_sel:DWORD src1_sel:BYTE_0
	v_and_b32_e32 v33, 0xff0000, v33
	v_and_b32_e32 v68, 0xff0000, v68
	v_or_b32_e32 v29, v31, v29
	v_or_b32_e32 v30, v30, v32
	v_or_b32_e32 v31, v29, v33
	v_or_b32_e32 v30, v30, v68
	global_store_dwordx2 v[8:9], v[30:31], off offset:3584
	v_lshlrev_b32_e32 v8, 16, v63
	v_and_b32_e32 v31, 0xffff0000, v65
	v_and_b32_e32 v30, 0xffff0000, v63
	v_lshlrev_b32_e32 v33, 16, v64
	v_lshlrev_b32_e32 v32, 16, v62
	v_and_b32_e32 v63, 0xffff0000, v64
	v_and_b32_e32 v62, 0xffff0000, v62
	v_lshlrev_b32_e32 v9, 16, v65
	v_pk_fma_f32 v[30:31], v[30:31], v[2:3], s[12:13] op_sel_hi:[1,0,0]
	v_pk_fma_f32 v[32:33], v[32:33], v[2:3], s[12:13] op_sel_hi:[1,0,0]
	v_pk_fma_f32 v[62:63], v[62:63], v[2:3], s[12:13] op_sel_hi:[1,0,0]
	v_pk_fma_f32 v[8:9], v[8:9], v[2:3], s[12:13] op_sel_hi:[1,0,0]
	v_lshlrev_b32_e32 v29, 8, v31
	v_lshlrev_b32_e32 v30, 8, v30
	v_lshlrev_b32_e32 v31, 16, v33
	v_lshlrev_b32_e32 v33, 24, v63
	v_lshlrev_b32_e32 v62, 24, v62
	v_and_b32_e32 v29, 0xff00, v29
	v_and_b32_e32 v30, 0xff00, v30
	v_lshlrev_b32_e32 v32, 16, v32
	v_or_b32_sdwa v9, v33, v9 dst_sel:DWORD dst_unused:UNUSED_PAD src0_sel:DWORD src1_sel:BYTE_0
; __device__ __forceinline__ float bf_lo(unsigned w) { return __uint_as_float(w << 16); }
; __device__ __forceinline__ float bf_hi(unsigned w) { return __uint_as_float(w & 0xffff0000u); }
; __device__ __forceinline__ unsigned q8_pack4(float a, float b, float c, float d, float inv) {
;     const unsigned ua = __float_as_uint(fmaf(a, inv, 12582912.0f)), ub = __float_as_uint(fmaf(b, inv, 12582912.0f)), uc = __float_as_uint(fmaf(c, inv, 12582912.0f)), ud = __float_as_uint(fmaf(d, inv, 12582912.0f));
;     return (ua & 255u) | ((ub & 255u) << 8) | ((uc & 255u) << 16) | (ud << 24);
;     ...
;         for (int i = 0; i < NC; ++i) { unsigned char* d = dst + (size_t)r * RL + 2048 * i + 8 * lane;
; #pragma unroll
;             for (int q = 0; q < 4; ++q) { const u32x4 w = pk[i][q]; u32x2 o; o.x = q8_pack4(bf_lo(w.x), bf_hi(w.x), bf_lo(w.y), bf_hi(w.y), inv); o.y = q8_pack4(bf_lo(w.z), bf_hi(w.z), bf_lo(w.w), bf_hi(w.w), inv);
;                 *(u32x2*)(d + 512 * q) = o; } } }
	v_or_b32_sdwa v8, v62, v8 dst_sel:DWORD dst_unused:UNUSED_PAD src0_sel:DWORD src1_sel:BYTE_0
	v_and_b32_e32 v31, 0xff0000, v31
	v_and_b32_e32 v32, 0xff0000, v32
	v_or_b32_e32 v9, v9, v29
	v_or_b32_e32 v8, v8, v30
	v_or_b32_e32 v9, v9, v31
	v_or_b32_e32 v8, v8, v32
	global_store_dwordx2 v[6:7], v[8:9], off
	v_lshlrev_b32_e32 v8, 16, v59
	v_and_b32_e32 v31, 0xffff0000, v61
	v_and_b32_e32 v30, 0xffff0000, v59
	v_lshlrev_b32_e32 v33, 16, v60
	v_lshlrev_b32_e32 v32, 16, v58
	v_and_b32_e32 v59, 0xffff0000, v60
	v_and_b32_e32 v58, 0xffff0000, v58
	v_lshlrev_b32_e32 v9, 16, v61
	v_pk_fma_f32 v[30:31], v[30:31], v[2:3], s[12:13] op_sel_hi:[1,0,0]
	v_pk_fma_f32 v[32:33], v[32:33], v[2:3], s[12:13] op_sel_hi:[1,0,0]
	v_pk_fma_f32 v[58:59], v[58:59], v[2:3], s[12:13] op_sel_hi:[1,0,0]
	v_pk_fma_f32 v[8:9], v[8:9], v[2:3], s[12:13] op_sel_hi:[1,0,0]
	v_lshlrev_b32_e32 v29, 8, v31
	v_lshlrev_b32_e32 v30, 8, v30
	v_lshlrev_b32_e32 v31, 16, v33
	v_lshlrev_b32_e32 v33, 24, v59
	v_lshlrev_b32_e32 v58, 24, v58
	v_and_b32_e32 v29, 0xff00, v29
	v_and_b32_e32 v30, 0xff00, v30
	v_lshlrev_b32_e32 v32, 16, v32
	v_or_b32_sdwa v9, v33, v9 dst_sel:DWORD dst_unused:UNUSED_PAD src0_sel:DWORD src1_sel:BYTE_0
	v_or_b32_sdwa v8, v58, v8 dst_sel:DWORD dst_unused:UNUSED_PAD src0_sel:DWORD src1_sel:BYTE_0
	v_and_b32_e32 v31, 0xff0000, v31
	v_and_b32_e32 v32, 0xff0000, v32
	v_or_b32_e32 v9, v9, v29
	v_or_b32_e32 v8, v8, v30
	v_or_b32_e32 v9, v9, v31
	v_or_b32_e32 v8, v8, v32
	global_store_dwordx2 v[6:7], v[8:9], off offset:512
	v_lshlrev_b32_e32 v8, 16, v55
	v_and_b32_e32 v31, 0xffff0000, v57
	v_and_b32_e32 v30, 0xffff0000, v55
	v_lshlrev_b32_e32 v33, 16, v56
	v_lshlrev_b32_e32 v32, 16, v54
	v_and_b32_e32 v55, 0xffff0000, v56
	v_and_b32_e32 v54, 0xffff0000, v54
	v_lshlrev_b32_e32 v9, 16, v57
	v_pk_fma_f32 v[30:31], v[30:31], v[2:3], s[12:13] op_sel_hi:[1,0,0]
	v_pk_fma_f32 v[32:33], v[32:33], v[2:3], s[12:13] op_sel_hi:[1,0,0]
	v_pk_fma_f32 v[54:55], v[54:55], v[2:3], s[12:13] op_sel_hi:[1,0,0]
	v_pk_fma_f32 v[8:9], v[8:9], v[2:3], s[12:13] op_sel_hi:[1,0,0]
	v_lshlrev_b32_e32 v29, 8, v31
	v_lshlrev_b32_e32 v30, 8, v30
	v_lshlrev_b32_e32 v31, 16, v33
	v_lshlrev_b32_e32 v33, 24, v55
	v_lshlrev_b32_e32 v54, 24, v54
	v_and_b32_e32 v29, 0xff00, v29
	v_and_b32_e32 v30, 0xff00, v30
	v_lshlrev_b32_e32 v32, 16, v32
	v_or_b32_sdwa v9, v33, v9 dst_sel:DWORD dst_unused:UNUSED_PAD src0_sel:DWORD src1_sel:BYTE_0
	v_or_b32_sdwa v8, v54, v8 dst_sel:DWORD dst_unused:UNUSED_PAD src0_sel:DWORD src1_sel:BYTE_0
	v_and_b32_e32 v31, 0xff0000, v31
	v_and_b32_e32 v32, 0xff0000, v32
	v_or_b32_e32 v9, v9, v29
	v_or_b32_e32 v8, v8, v30
	v_or_b32_e32 v9, v9, v31
	v_or_b32_e32 v8, v8, v32
	global_store_dwordx2 v[6:7], v[8:9], off offset:1024
	v_lshlrev_b32_e32 v8, 16, v51
	v_and_b32_e32 v31, 0xffff0000, v53
	v_and_b32_e32 v30, 0xffff0000, v51
	v_lshlrev_b32_e32 v33, 16, v52
	v_lshlrev_b32_e32 v32, 16, v50
	v_and_b32_e32 v51, 0xffff0000, v52
	v_and_b32_e32 v50, 0xffff0000, v50
	v_lshlrev_b32_e32 v9, 16, v53
	v_pk_fma_f32 v[30:31], v[30:31], v[2:3], s[12:13] op_sel_hi:[1,0,0]
	v_pk_fma_f32 v[32:33], v[32:33], v[2:3], s[12:13] op_sel_hi:[1,0,0]
	v_pk_fma_f32 v[50:51], v[50:51], v[2:3], s[12:13] op_sel_hi:[1,0,0]
	v_pk_fma_f32 v[8:9], v[8:9], v[2:3], s[12:13] op_sel_hi:[1,0,0]
	v_lshlrev_b32_e32 v29, 8, v31
	v_lshlrev_b32_e32 v30, 8, v30
	v_lshlrev_b32_e32 v31, 16, v33
	v_lshlrev_b32_e32 v33, 24, v51
	v_lshlrev_b32_e32 v50, 24, v50
	v_and_b32_e32 v29, 0xff00, v29
	v_and_b32_e32 v30, 0xff00, v30
	v_lshlrev_b32_e32 v32, 16, v32
	v_or_b32_sdwa v9, v33, v9 dst_sel:DWORD dst_unused:UNUSED_PAD src0_sel:DWORD src1_sel:BYTE_0
	v_or_b32_sdwa v8, v50, v8 dst_sel:DWORD dst_unused:UNUSED_PAD src0_sel:DWORD src1_sel:BYTE_0
	v_and_b32_e32 v31, 0xff0000, v31
	v_and_b32_e32 v32, 0xff0000, v32
	v_or_b32_e32 v9, v9, v29
	v_or_b32_e32 v8, v8, v30
	v_or_b32_e32 v9, v9, v31
	v_or_b32_e32 v8, v8, v32
	global_store_dwordx2 v[6:7], v[8:9], off offset:1536
	v_lshlrev_b32_e32 v8, 16, v47
	v_and_b32_e32 v31, 0xffff0000, v49
	v_and_b32_e32 v30, 0xffff0000, v47
	v_lshlrev_b32_e32 v33, 16, v48
	v_lshlrev_b32_e32 v32, 16, v46
	v_and_b32_e32 v47, 0xffff0000, v48
	v_and_b32_e32 v46, 0xffff0000, v46
	v_lshlrev_b32_e32 v9, 16, v49
	v_pk_fma_f32 v[30:31], v[30:31], v[2:3], s[12:13] op_sel_hi:[1,0,0]
	v_pk_fma_f32 v[32:33], v[32:33], v[2:3], s[12:13] op_sel_hi:[1,0,0]
	v_pk_fma_f32 v[46:47], v[46:47], v[2:3], s[12:13] op_sel_hi:[1,0,0]
	v_pk_fma_f32 v[8:9], v[8:9], v[2:3], s[12:13] op_sel_hi:[1,0,0]
	v_lshlrev_b32_e32 v29, 8, v31
	v_lshlrev_b32_e32 v30, 8, v30
	v_lshlrev_b32_e32 v31, 16, v33
	v_lshlrev_b32_e32 v33, 24, v47
	v_lshlrev_b32_e32 v46, 24, v46
	v_and_b32_e32 v29, 0xff00, v29
	v_and_b32_e32 v30, 0xff00, v30
	v_lshlrev_b32_e32 v32, 16, v32
	v_or_b32_sdwa v9, v33, v9 dst_sel:DWORD dst_unused:UNUSED_PAD src0_sel:DWORD src1_sel:BYTE_0
	v_or_b32_sdwa v8, v46, v8 dst_sel:DWORD dst_unused:UNUSED_PAD src0_sel:DWORD src1_sel:BYTE_0
	v_and_b32_e32 v31, 0xff0000, v31
	v_and_b32_e32 v32, 0xff0000, v32
	v_or_b32_e32 v9, v9, v29
	v_or_b32_e32 v8, v8, v30
	v_or_b32_e32 v9, v9, v31
	v_or_b32_e32 v8, v8, v32
	global_store_dwordx2 v[6:7], v[8:9], off offset:2048
	v_lshlrev_b32_e32 v8, 16, v43
	v_and_b32_e32 v31, 0xffff0000, v45
	v_and_b32_e32 v30, 0xffff0000, v43
	v_lshlrev_b32_e32 v33, 16, v44
	v_lshlrev_b32_e32 v32, 16, v42
	v_and_b32_e32 v43, 0xffff0000, v44
	v_and_b32_e32 v42, 0xffff0000, v42
	v_lshlrev_b32_e32 v9, 16, v45
	v_pk_fma_f32 v[30:31], v[30:31], v[2:3], s[12:13] op_sel_hi:[1,0,0]
	v_pk_fma_f32 v[32:33], v[32:33], v[2:3], s[12:13] op_sel_hi:[1,0,0]
	v_pk_fma_f32 v[42:43], v[42:43], v[2:3], s[12:13] op_sel_hi:[1,0,0]
; __device__ __forceinline__ float bf_lo(unsigned w) { return __uint_as_float(w << 16); }
; __device__ __forceinline__ float bf_hi(unsigned w) { return __uint_as_float(w & 0xffff0000u); }
; __device__ __forceinline__ unsigned q8_pack4(float a, float b, float c, float d, float inv) {
;     const unsigned ua = __float_as_uint(fmaf(a, inv, 12582912.0f)), ub = __float_as_uint(fmaf(b, inv, 12582912.0f)), uc = __float_as_uint(fmaf(c, inv, 12582912.0f)), ud = __float_as_uint(fmaf(d, inv, 12582912.0f));
;     return (ua & 255u) | ((ub & 255u) << 8) | ((uc & 255u) << 16) | (ud << 24);
;     ...
;         for (int i = 0; i < NC; ++i) { unsigned char* d = dst + (size_t)r * RL + 2048 * i + 8 * lane;
; #pragma unroll
;             for (int q = 0; q < 4; ++q) { const u32x4 w = pk[i][q]; u32x2 o; o.x = q8_pack4(bf_lo(w.x), bf_hi(w.x), bf_lo(w.y), bf_hi(w.y), inv); o.y = q8_pack4(bf_lo(w.z), bf_hi(w.z), bf_lo(w.w), bf_hi(w.w), inv);
;                 *(u32x2*)(d + 512 * q) = o; } } }
	v_pk_fma_f32 v[8:9], v[8:9], v[2:3], s[12:13] op_sel_hi:[1,0,0]
	v_lshlrev_b32_e32 v29, 8, v31
	v_lshlrev_b32_e32 v30, 8, v30
	v_lshlrev_b32_e32 v31, 16, v33
	v_lshlrev_b32_e32 v33, 24, v43
	v_lshlrev_b32_e32 v42, 24, v42
	v_and_b32_e32 v29, 0xff00, v29
	v_and_b32_e32 v30, 0xff00, v30
	v_lshlrev_b32_e32 v32, 16, v32
	v_or_b32_sdwa v9, v33, v9 dst_sel:DWORD dst_unused:UNUSED_PAD src0_sel:DWORD src1_sel:BYTE_0
	v_or_b32_sdwa v8, v42, v8 dst_sel:DWORD dst_unused:UNUSED_PAD src0_sel:DWORD src1_sel:BYTE_0
	v_and_b32_e32 v31, 0xff0000, v31
	v_and_b32_e32 v32, 0xff0000, v32
	v_or_b32_e32 v9, v9, v29
	v_or_b32_e32 v8, v8, v30
	v_or_b32_e32 v9, v9, v31
	v_or_b32_e32 v8, v8, v32
	global_store_dwordx2 v[6:7], v[8:9], off offset:2560
	v_lshlrev_b32_e32 v8, 16, v39
	v_and_b32_e32 v31, 0xffff0000, v41
	v_and_b32_e32 v30, 0xffff0000, v39
	v_lshlrev_b32_e32 v33, 16, v40
	v_lshlrev_b32_e32 v32, 16, v38
	v_and_b32_e32 v39, 0xffff0000, v40
	v_and_b32_e32 v38, 0xffff0000, v38
	v_lshlrev_b32_e32 v9, 16, v41
	v_pk_fma_f32 v[30:31], v[30:31], v[2:3], s[12:13] op_sel_hi:[1,0,0]
	v_pk_fma_f32 v[32:33], v[32:33], v[2:3], s[12:13] op_sel_hi:[1,0,0]
	v_pk_fma_f32 v[38:39], v[38:39], v[2:3], s[12:13] op_sel_hi:[1,0,0]
	v_pk_fma_f32 v[8:9], v[8:9], v[2:3], s[12:13] op_sel_hi:[1,0,0]
	v_lshlrev_b32_e32 v29, 8, v31
	v_lshlrev_b32_e32 v30, 8, v30
	v_lshlrev_b32_e32 v31, 16, v33
	v_lshlrev_b32_e32 v33, 24, v39
	v_lshlrev_b32_e32 v38, 24, v38
	v_and_b32_e32 v29, 0xff00, v29
	v_and_b32_e32 v30, 0xff00, v30
	v_lshlrev_b32_e32 v32, 16, v32
	v_or_b32_sdwa v9, v33, v9 dst_sel:DWORD dst_unused:UNUSED_PAD src0_sel:DWORD src1_sel:BYTE_0
	v_or_b32_sdwa v8, v38, v8 dst_sel:DWORD dst_unused:UNUSED_PAD src0_sel:DWORD src1_sel:BYTE_0
	v_and_b32_e32 v31, 0xff0000, v31
	v_and_b32_e32 v32, 0xff0000, v32
	v_or_b32_e32 v9, v9, v29
	v_or_b32_e32 v8, v8, v30
	v_or_b32_e32 v9, v9, v31
	v_or_b32_e32 v8, v8, v32
	global_store_dwordx2 v[6:7], v[8:9], off offset:3072
	v_lshlrev_b32_e32 v8, 16, v35
	v_and_b32_e32 v31, 0xffff0000, v37
	v_and_b32_e32 v30, 0xffff0000, v35
	v_lshlrev_b32_e32 v33, 16, v36
	v_lshlrev_b32_e32 v32, 16, v34
	v_and_b32_e32 v35, 0xffff0000, v36
	v_and_b32_e32 v34, 0xffff0000, v34
	v_lshlrev_b32_e32 v9, 16, v37
	v_pk_fma_f32 v[30:31], v[30:31], v[2:3], s[12:13] op_sel_hi:[1,0,0]
	v_pk_fma_f32 v[32:33], v[32:33], v[2:3], s[12:13] op_sel_hi:[1,0,0]
	v_pk_fma_f32 v[34:35], v[34:35], v[2:3], s[12:13] op_sel_hi:[1,0,0]
	v_pk_fma_f32 v[8:9], v[8:9], v[2:3], s[12:13] op_sel_hi:[1,0,0]
	v_lshlrev_b32_e32 v29, 8, v31
	v_lshlrev_b32_e32 v30, 8, v30
	v_lshlrev_b32_e32 v31, 16, v33
	v_lshlrev_b32_e32 v33, 24, v35
	v_lshlrev_b32_e32 v34, 24, v34
	v_and_b32_e32 v29, 0xff00, v29
	v_and_b32_e32 v30, 0xff00, v30
	v_lshlrev_b32_e32 v32, 16, v32
	v_or_b32_sdwa v9, v33, v9 dst_sel:DWORD dst_unused:UNUSED_PAD src0_sel:DWORD src1_sel:BYTE_0
	v_or_b32_sdwa v8, v34, v8 dst_sel:DWORD dst_unused:UNUSED_PAD src0_sel:DWORD src1_sel:BYTE_0
	v_and_b32_e32 v31, 0xff0000, v31
	v_and_b32_e32 v32, 0xff0000, v32
	v_or_b32_e32 v9, v9, v29
	v_or_b32_e32 v8, v8, v30
	v_or_b32_e32 v9, v9, v31
	v_or_b32_e32 v8, v8, v32
	global_store_dwordx2 v[6:7], v[8:9], off offset:3584
	v_and_b32_e32 v9, 0xffff0000, v117
	v_and_b32_e32 v8, 0xffff0000, v115
	v_lshlrev_b32_e32 v31, 16, v116
	v_lshlrev_b32_e32 v30, 16, v114
	v_and_b32_e32 v33, 0xffff0000, v116
	v_and_b32_e32 v32, 0xffff0000, v114
	v_lshlrev_b32_e32 v7, 16, v117
	v_lshlrev_b32_e32 v6, 16, v115
	v_pk_fma_f32 v[8:9], v[8:9], v[2:3], s[12:13] op_sel_hi:[1,0,0]
	v_pk_fma_f32 v[30:31], v[30:31], v[2:3], s[12:13] op_sel_hi:[1,0,0]
	v_pk_fma_f32 v[32:33], v[32:33], v[2:3], s[12:13] op_sel_hi:[1,0,0]
	v_pk_fma_f32 v[6:7], v[6:7], v[2:3], s[12:13] op_sel_hi:[1,0,0]
	v_lshlrev_b32_e32 v9, 8, v9
	v_lshlrev_b32_e32 v8, 8, v8
	v_lshlrev_b32_e32 v29, 16, v31
	v_lshlrev_b32_e32 v31, 24, v33
	v_lshlrev_b32_e32 v32, 24, v32
	v_and_b32_e32 v9, 0xff00, v9
	v_and_b32_e32 v8, 0xff00, v8
	v_lshlrev_b32_e32 v30, 16, v30
	v_or_b32_sdwa v7, v31, v7 dst_sel:DWORD dst_unused:UNUSED_PAD src0_sel:DWORD src1_sel:BYTE_0
	v_or_b32_sdwa v6, v32, v6 dst_sel:DWORD dst_unused:UNUSED_PAD src0_sel:DWORD src1_sel:BYTE_0
	v_and_b32_e32 v29, 0xff0000, v29
	v_and_b32_e32 v30, 0xff0000, v30
	v_or_b32_e32 v7, v7, v9
	v_or_b32_e32 v6, v6, v8
	v_add_co_u32_e32 v4, vcc, s20, v4
	v_or_b32_e32 v7, v7, v29
	v_or_b32_e32 v6, v6, v30
	v_addc_co_u32_e32 v5, vcc, 0, v5, vcc
	v_and_b32_e32 v9, 0xffff0000, v113
	v_and_b32_e32 v8, 0xffff0000, v111
	v_lshlrev_b32_e32 v31, 16, v112
	v_lshlrev_b32_e32 v30, 16, v110
	v_and_b32_e32 v33, 0xffff0000, v112
	v_and_b32_e32 v32, 0xffff0000, v110
	global_store_dwordx2 v[4:5], v[6:7], off
	v_lshlrev_b32_e32 v7, 16, v113
	v_lshlrev_b32_e32 v6, 16, v111
	v_pk_fma_f32 v[8:9], v[8:9], v[2:3], s[12:13] op_sel_hi:[1,0,0]
	v_pk_fma_f32 v[30:31], v[30:31], v[2:3], s[12:13] op_sel_hi:[1,0,0]
	v_pk_fma_f32 v[32:33], v[32:33], v[2:3], s[12:13] op_sel_hi:[1,0,0]
	v_pk_fma_f32 v[6:7], v[6:7], v[2:3], s[12:13] op_sel_hi:[1,0,0]
	v_lshlrev_b32_e32 v9, 8, v9
	v_lshlrev_b32_e32 v8, 8, v8
	v_lshlrev_b32_e32 v29, 16, v31
	v_lshlrev_b32_e32 v31, 24, v33
	v_lshlrev_b32_e32 v32, 24, v32
	v_and_b32_e32 v9, 0xff00, v9
	v_and_b32_e32 v8, 0xff00, v8
	v_lshlrev_b32_e32 v30, 16, v30
	v_or_b32_sdwa v7, v31, v7 dst_sel:DWORD dst_unused:UNUSED_PAD src0_sel:DWORD src1_sel:BYTE_0
	v_or_b32_sdwa v6, v32, v6 dst_sel:DWORD dst_unused:UNUSED_PAD src0_sel:DWORD src1_sel:BYTE_0
	v_and_b32_e32 v29, 0xff0000, v29
	v_and_b32_e32 v30, 0xff0000, v30
	v_or_b32_e32 v7, v7, v9
	v_or_b32_e32 v6, v6, v8
	v_or_b32_e32 v7, v7, v29
	v_or_b32_e32 v6, v6, v30
	v_and_b32_e32 v9, 0xffff0000, v121
	v_and_b32_e32 v8, 0xffff0000, v120
; __device__ __forceinline__ float bf_lo(unsigned w) { return __uint_as_float(w << 16); }
; __device__ __forceinline__ float bf_hi(unsigned w) { return __uint_as_float(w & 0xffff0000u); }
; __device__ __forceinline__ unsigned q8_pack4(float a, float b, float c, float d, float inv) {
;     const unsigned ua = __float_as_uint(fmaf(a, inv, 12582912.0f)), ub = __float_as_uint(fmaf(b, inv, 12582912.0f)), uc = __float_as_uint(fmaf(c, inv, 12582912.0f)), ud = __float_as_uint(fmaf(d, inv, 12582912.0f));
;     return (ua & 255u) | ((ub & 255u) << 8) | ((uc & 255u) << 16) | (ud << 24);
;     ...
;         for (int i = 0; i < NC; ++i) { unsigned char* d = dst + (size_t)r * RL + 2048 * i + 8 * lane;
; #pragma unroll
;             for (int q = 0; q < 4; ++q) { const u32x4 w = pk[i][q]; u32x2 o; o.x = q8_pack4(bf_lo(w.x), bf_hi(w.x), bf_lo(w.y), bf_hi(w.y), inv); o.y = q8_pack4(bf_lo(w.z), bf_hi(w.z), bf_lo(w.w), bf_hi(w.w), inv);
;                 *(u32x2*)(d + 512 * q) = o; } } }
	v_lshlrev_b32_e32 v31, 16, v119
	v_lshlrev_b32_e32 v30, 16, v118
	v_and_b32_e32 v33, 0xffff0000, v119
	v_and_b32_e32 v32, 0xffff0000, v118
	global_store_dwordx2 v[4:5], v[6:7], off offset:512
	v_lshlrev_b32_e32 v7, 16, v121
	v_lshlrev_b32_e32 v6, 16, v120
	v_pk_fma_f32 v[8:9], v[8:9], v[2:3], s[12:13] op_sel_hi:[1,0,0]
	v_pk_fma_f32 v[30:31], v[30:31], v[2:3], s[12:13] op_sel_hi:[1,0,0]
	v_pk_fma_f32 v[32:33], v[32:33], v[2:3], s[12:13] op_sel_hi:[1,0,0]
	v_pk_fma_f32 v[6:7], v[6:7], v[2:3], s[12:13] op_sel_hi:[1,0,0]
	v_lshlrev_b32_e32 v9, 8, v9
	v_lshlrev_b32_e32 v8, 8, v8
	v_lshlrev_b32_e32 v29, 16, v31
	v_lshlrev_b32_e32 v31, 24, v33
	v_lshlrev_b32_e32 v32, 24, v32
	v_and_b32_e32 v9, 0xff00, v9
	v_and_b32_e32 v8, 0xff00, v8
	v_lshlrev_b32_e32 v30, 16, v30
	v_or_b32_sdwa v7, v31, v7 dst_sel:DWORD dst_unused:UNUSED_PAD src0_sel:DWORD src1_sel:BYTE_0
	v_or_b32_sdwa v6, v32, v6 dst_sel:DWORD dst_unused:UNUSED_PAD src0_sel:DWORD src1_sel:BYTE_0
	v_and_b32_e32 v29, 0xff0000, v29
	v_and_b32_e32 v30, 0xff0000, v30
	v_or_b32_e32 v7, v7, v9
	v_or_b32_e32 v6, v6, v8
	v_or_b32_e32 v7, v7, v29
	v_or_b32_e32 v6, v6, v30
	global_store_dwordx2 v[4:5], v[6:7], off offset:1024
	v_lshlrev_b32_e32 v6, 16, v27
	v_and_b32_e32 v9, 0xffff0000, v28
	v_and_b32_e32 v8, 0xffff0000, v27
	v_lshlrev_b32_e32 v29, 16, v26
	v_and_b32_e32 v27, 0xffff0000, v26
	v_and_b32_e32 v26, 0xffff0000, v25
	v_lshlrev_b32_e32 v7, 16, v28
	v_lshlrev_b32_e32 v28, 16, v25
	v_pk_fma_f32 v[8:9], v[8:9], v[2:3], s[12:13] op_sel_hi:[1,0,0]
	v_pk_fma_f32 v[26:27], v[26:27], v[2:3], s[12:13] op_sel_hi:[1,0,0]
	v_pk_fma_f32 v[6:7], v[6:7], v[2:3], s[12:13] op_sel_hi:[1,0,0]
	v_pk_fma_f32 v[28:29], v[28:29], v[2:3], s[12:13] op_sel_hi:[1,0,0]
	v_lshlrev_b32_e32 v9, 8, v9
	v_lshlrev_b32_e32 v8, 8, v8
	v_lshlrev_b32_e32 v27, 24, v27
	v_lshlrev_b32_e32 v26, 24, v26
	v_and_b32_e32 v9, 0xff00, v9
	v_and_b32_e32 v8, 0xff00, v8
	v_lshlrev_b32_e32 v25, 16, v29
	v_lshlrev_b32_e32 v28, 16, v28
	v_or_b32_sdwa v7, v27, v7 dst_sel:DWORD dst_unused:UNUSED_PAD src0_sel:DWORD src1_sel:BYTE_0
	v_or_b32_sdwa v6, v26, v6 dst_sel:DWORD dst_unused:UNUSED_PAD src0_sel:DWORD src1_sel:BYTE_0
	v_and_b32_e32 v25, 0xff0000, v25
	v_and_b32_e32 v28, 0xff0000, v28
	v_or_b32_e32 v7, v7, v9
	v_or_b32_e32 v6, v6, v8
	v_or_b32_e32 v7, v7, v25
	v_or_b32_e32 v6, v6, v28
	global_store_dwordx2 v[4:5], v[6:7], off offset:1536
	v_lshlrev_b32_e32 v6, 16, v23
	v_and_b32_e32 v9, 0xffff0000, v24
	v_and_b32_e32 v8, 0xffff0000, v23
	v_lshlrev_b32_e32 v25, 16, v22
	v_and_b32_e32 v23, 0xffff0000, v22
	v_and_b32_e32 v22, 0xffff0000, v21
	v_lshlrev_b32_e32 v7, 16, v24
	v_lshlrev_b32_e32 v24, 16, v21
	v_pk_fma_f32 v[8:9], v[8:9], v[2:3], s[12:13] op_sel_hi:[1,0,0]
	v_pk_fma_f32 v[22:23], v[22:23], v[2:3], s[12:13] op_sel_hi:[1,0,0]
	v_pk_fma_f32 v[6:7], v[6:7], v[2:3], s[12:13] op_sel_hi:[1,0,0]
	v_pk_fma_f32 v[24:25], v[24:25], v[2:3], s[12:13] op_sel_hi:[1,0,0]
	v_lshlrev_b32_e32 v9, 8, v9
	v_lshlrev_b32_e32 v8, 8, v8
	v_lshlrev_b32_e32 v23, 24, v23
	v_lshlrev_b32_e32 v22, 24, v22
	v_and_b32_e32 v9, 0xff00, v9
	v_and_b32_e32 v8, 0xff00, v8
	v_lshlrev_b32_e32 v21, 16, v25
	v_lshlrev_b32_e32 v24, 16, v24
	v_or_b32_sdwa v7, v23, v7 dst_sel:DWORD dst_unused:UNUSED_PAD src0_sel:DWORD src1_sel:BYTE_0
	v_or_b32_sdwa v6, v22, v6 dst_sel:DWORD dst_unused:UNUSED_PAD src0_sel:DWORD src1_sel:BYTE_0
	v_and_b32_e32 v21, 0xff0000, v21
	v_and_b32_e32 v24, 0xff0000, v24
	v_or_b32_e32 v7, v7, v9
	v_or_b32_e32 v6, v6, v8
	v_or_b32_e32 v7, v7, v21
	v_or_b32_e32 v6, v6, v24
	global_store_dwordx2 v[4:5], v[6:7], off offset:2048
	v_lshlrev_b32_e32 v6, 16, v19
	v_and_b32_e32 v9, 0xffff0000, v20
	v_and_b32_e32 v8, 0xffff0000, v19
; __device__ __forceinline__ float bf_lo(unsigned w) { return __uint_as_float(w << 16); }
; __device__ __forceinline__ float bf_hi(unsigned w) { return __uint_as_float(w & 0xffff0000u); }
;     ...
;     for (int r = gw; r < R; r += NGW) { const bf16_t* sr = src + (size_t)r * RL; u32x4 pk[NC][4]; float mx = 0.f;
;     ...
;         for (int i = 0; i < NC; ++i) { unsigned char* d = dst + (size_t)r * RL + 2048 * i + 8 * lane;
; #pragma unroll
;             for (int q = 0; q < 4; ++q) { const u32x4 w = pk[i][q]; u32x2 o; o.x = q8_pack4(bf_lo(w.x), bf_hi(w.x), bf_lo(w.y), bf_hi(w.y), inv); o.y = q8_pack4(bf_lo(w.z), bf_hi(w.z), bf_lo(w.w), bf_hi(w.w), inv);
;                 *(u32x2*)(d + 512 * q) = o; } } }
	v_lshlrev_b32_e32 v21, 16, v18
	v_and_b32_e32 v19, 0xffff0000, v18
	v_and_b32_e32 v18, 0xffff0000, v17
	v_lshlrev_b32_e32 v7, 16, v20
	v_lshlrev_b32_e32 v20, 16, v17
	v_pk_fma_f32 v[8:9], v[8:9], v[2:3], s[12:13] op_sel_hi:[1,0,0]
	v_pk_fma_f32 v[18:19], v[18:19], v[2:3], s[12:13] op_sel_hi:[1,0,0]
	v_pk_fma_f32 v[6:7], v[6:7], v[2:3], s[12:13] op_sel_hi:[1,0,0]
	v_pk_fma_f32 v[20:21], v[20:21], v[2:3], s[12:13] op_sel_hi:[1,0,0]
	v_lshlrev_b32_e32 v9, 8, v9
	v_lshlrev_b32_e32 v8, 8, v8
	v_lshlrev_b32_e32 v19, 24, v19
	v_lshlrev_b32_e32 v18, 24, v18
	v_and_b32_e32 v9, 0xff00, v9
	v_and_b32_e32 v8, 0xff00, v8
	v_lshlrev_b32_e32 v17, 16, v21
	v_lshlrev_b32_e32 v20, 16, v20
	v_or_b32_sdwa v7, v19, v7 dst_sel:DWORD dst_unused:UNUSED_PAD src0_sel:DWORD src1_sel:BYTE_0
	v_or_b32_sdwa v6, v18, v6 dst_sel:DWORD dst_unused:UNUSED_PAD src0_sel:DWORD src1_sel:BYTE_0
	v_and_b32_e32 v17, 0xff0000, v17
	v_and_b32_e32 v20, 0xff0000, v20
	v_or_b32_e32 v7, v7, v9
	v_or_b32_e32 v6, v6, v8
	v_or_b32_e32 v7, v7, v17
	v_or_b32_e32 v6, v6, v20
	global_store_dwordx2 v[4:5], v[6:7], off offset:2560
	v_lshlrev_b32_e32 v6, 16, v15
	v_and_b32_e32 v9, 0xffff0000, v16
	v_and_b32_e32 v8, 0xffff0000, v15
	v_lshlrev_b32_e32 v17, 16, v14
	v_and_b32_e32 v15, 0xffff0000, v14
	v_and_b32_e32 v14, 0xffff0000, v13
	v_lshlrev_b32_e32 v7, 16, v16
	v_lshlrev_b32_e32 v16, 16, v13
	v_pk_fma_f32 v[8:9], v[8:9], v[2:3], s[12:13] op_sel_hi:[1,0,0]
	v_pk_fma_f32 v[14:15], v[14:15], v[2:3], s[12:13] op_sel_hi:[1,0,0]
	v_pk_fma_f32 v[6:7], v[6:7], v[2:3], s[12:13] op_sel_hi:[1,0,0]
	v_pk_fma_f32 v[16:17], v[16:17], v[2:3], s[12:13] op_sel_hi:[1,0,0]
	v_lshlrev_b32_e32 v9, 8, v9
	v_lshlrev_b32_e32 v8, 8, v8
	v_lshlrev_b32_e32 v15, 24, v15
	v_lshlrev_b32_e32 v14, 24, v14
	v_and_b32_e32 v9, 0xff00, v9
	v_and_b32_e32 v8, 0xff00, v8
	v_lshlrev_b32_e32 v13, 16, v17
	v_lshlrev_b32_e32 v16, 16, v16
	v_or_b32_sdwa v7, v15, v7 dst_sel:DWORD dst_unused:UNUSED_PAD src0_sel:DWORD src1_sel:BYTE_0
	v_or_b32_sdwa v6, v14, v6 dst_sel:DWORD dst_unused:UNUSED_PAD src0_sel:DWORD src1_sel:BYTE_0
	v_and_b32_e32 v13, 0xff0000, v13
	v_and_b32_e32 v16, 0xff0000, v16
	v_or_b32_e32 v7, v7, v9
	v_or_b32_e32 v6, v6, v8
	v_or_b32_e32 v7, v7, v13
	v_or_b32_e32 v6, v6, v16
	global_store_dwordx2 v[4:5], v[6:7], off offset:3072
	v_lshlrev_b32_e32 v7, 16, v12
	v_lshlrev_b32_e32 v6, 16, v11
	v_and_b32_e32 v9, 0xffff0000, v12
	v_and_b32_e32 v8, 0xffff0000, v11
	v_lshlrev_b32_e32 v13, 16, v10
	v_lshlrev_b32_e32 v12, 16, v3
	v_and_b32_e32 v11, 0xffff0000, v10
	v_and_b32_e32 v10, 0xffff0000, v3
	v_pk_fma_f32 v[6:7], v[6:7], v[2:3], s[12:13] op_sel_hi:[1,0,0]
	v_pk_fma_f32 v[8:9], v[8:9], v[2:3], s[12:13] op_sel_hi:[1,0,0]
	v_pk_fma_f32 v[12:13], v[12:13], v[2:3], s[12:13] op_sel_hi:[1,0,0]
	v_pk_fma_f32 v[2:3], v[10:11], v[2:3], s[12:13] op_sel_hi:[1,0,0]
	v_lshlrev_b32_e32 v9, 8, v9
	v_lshlrev_b32_e32 v8, 8, v8
	v_lshlrev_b32_e32 v3, 24, v3
	v_lshlrev_b32_e32 v2, 24, v2
	s_add_i32 s13, s13, s2
	v_and_b32_e32 v9, 0xff00, v9
	v_and_b32_e32 v8, 0xff00, v8
	v_lshlrev_b32_e32 v10, 16, v13
	v_lshlrev_b32_e32 v11, 16, v12
	v_or_b32_sdwa v3, v3, v7 dst_sel:DWORD dst_unused:UNUSED_PAD src0_sel:DWORD src1_sel:BYTE_0
	v_or_b32_sdwa v2, v2, v6 dst_sel:DWORD dst_unused:UNUSED_PAD src0_sel:DWORD src1_sel:BYTE_0
	s_add_u32 s16, s16, s6
	v_and_b32_e32 v10, 0xff0000, v10
	v_and_b32_e32 v11, 0xff0000, v11
	v_or_b32_e32 v3, v3, v9
	v_or_b32_e32 v2, v2, v8
	s_addc_u32 s17, s17, s7
	v_or_b32_e32 v3, v3, v10
	v_or_b32_e32 v2, v2, v11
	v_lshl_add_u64 v[82:83], v[82:83], 0, s[8:9]
	s_cmp_lt_u32 s13, 0x2200
	v_lshl_add_u64 v[84:85], v[84:85], 0, s[10:11]
	global_store_dwordx2 v[4:5], v[2:3], off offset:3584
	s_cbranch_scc0 .LBB0_2804
